# mod_job k-loop rewritten: 24 loads per thread in flight (on top of v20)
# speedup vs baseline: 1.0021x; 1.0020x over previous
.LBB0_28:
	s_mul_hi_i32 s6, s12, 0x2aaaaaab
	s_lshr_b32 s7, s6, 31
	s_ashr_i32 s6, s6, 3
	s_add_i32 s6, s6, s7
	s_mul_i32 s7, s6, 48
	s_sub_i32 s7, s12, s7
	s_lshl_b32 s8, s7, 6
	s_ashr_i32 s7, s6, 31
	s_lshl_b64 s[10:11], s[6:7], 10
	v_lshl_add_u64 v[4:5], s[10:11], 0, v[22:23]
	v_or_b32_e32 v2, s8, v1
	v_mad_u64_u32 v[6:7], s[10:11], v4, s14, v[32:33]
	v_mad_i32_i24 v7, v5, s14, v7
	v_ashrrev_i32_e32 v3, 31, v2
	v_lshl_add_u64 v[36:37], v[2:3], 2, v[6:7]
	v_mov_b32_e32 v2, 0
	s_mov_b64 s[10:11], 0
	v_mov_b32_e32 v45, v38
	v_mov_b32_e32 v3, v2
	v_mov_b32_e32 v4, v2
	v_mov_b32_e32 v5, v2
	v_mov_b32_e32 v6, v2
	v_mov_b32_e32 v7, v2
	v_mov_b32_e32 v8, v2
	v_mov_b32_e32 v9, v2
	v_mov_b32_e32 v122, v36
	v_mov_b32_e32 v123, v37
	s_mov_b32 s10, 0x3000
	s_mov_b32 s11, 0
	v_lshl_add_u64 v[124:125], v[122:123], 0, s[10:11]
	v_lshl_add_u64 v[126:127], v[124:125], 0, s[10:11]
	v_lshl_add_u64 v[128:129], v[126:127], 0, s[10:11]
	v_lshl_add_u64 v[130:131], v[128:129], 0, s[10:11]
	v_lshl_add_u64 v[132:133], v[130:131], 0, s[10:11]
	v_lshl_add_u64 v[134:135], v[132:133], 0, s[10:11]
	v_lshl_add_u64 v[136:137], v[134:135], 0, s[10:11]
	s_mov_b32 s10, 0x18000
	global_load_dword v138, v[122:123], off
	global_load_dword v139, v[124:125], off
	global_load_dword v140, v[126:127], off
	global_load_dword v141, v[128:129], off
	global_load_dword v142, v[130:131], off
	global_load_dword v143, v[132:133], off
	global_load_dword v144, v[134:135], off
	global_load_dword v145, v[136:137], off
	v_lshl_add_u64 v[122:123], v[122:123], 0, s[10:11]
	v_lshl_add_u64 v[124:125], v[124:125], 0, s[10:11]
	v_lshl_add_u64 v[126:127], v[126:127], 0, s[10:11]
	v_lshl_add_u64 v[128:129], v[128:129], 0, s[10:11]
	v_lshl_add_u64 v[130:131], v[130:131], 0, s[10:11]
	v_lshl_add_u64 v[132:133], v[132:133], 0, s[10:11]
	v_lshl_add_u64 v[134:135], v[134:135], 0, s[10:11]
	v_lshl_add_u64 v[136:137], v[136:137], 0, s[10:11]
	global_load_dword v146, v[122:123], off
	global_load_dword v147, v[124:125], off
	global_load_dword v148, v[126:127], off
	global_load_dword v149, v[128:129], off
	global_load_dword v150, v[130:131], off
	global_load_dword v151, v[132:133], off
	global_load_dword v152, v[134:135], off
	global_load_dword v153, v[136:137], off
	v_lshl_add_u64 v[122:123], v[122:123], 0, s[10:11]
	v_lshl_add_u64 v[124:125], v[124:125], 0, s[10:11]
	v_lshl_add_u64 v[126:127], v[126:127], 0, s[10:11]
	v_lshl_add_u64 v[128:129], v[128:129], 0, s[10:11]
	v_lshl_add_u64 v[130:131], v[130:131], 0, s[10:11]
	v_lshl_add_u64 v[132:133], v[132:133], 0, s[10:11]
	v_lshl_add_u64 v[134:135], v[134:135], 0, s[10:11]
	v_lshl_add_u64 v[136:137], v[136:137], 0, s[10:11]
	global_load_dword v154, v[122:123], off
	global_load_dword v155, v[124:125], off
	global_load_dword v156, v[126:127], off
	global_load_dword v157, v[128:129], off
	global_load_dword v158, v[130:131], off
	global_load_dword v159, v[132:133], off
	global_load_dword v160, v[134:135], off
	global_load_dword v161, v[136:137], off
	v_lshl_add_u64 v[122:123], v[122:123], 0, s[10:11]
	v_lshl_add_u64 v[124:125], v[124:125], 0, s[10:11]
	v_lshl_add_u64 v[126:127], v[126:127], 0, s[10:11]
	v_lshl_add_u64 v[128:129], v[128:129], 0, s[10:11]
	v_lshl_add_u64 v[130:131], v[130:131], 0, s[10:11]
	v_lshl_add_u64 v[132:133], v[132:133], 0, s[10:11]
	v_lshl_add_u64 v[134:135], v[134:135], 0, s[10:11]
	v_lshl_add_u64 v[136:137], v[136:137], 0, s[10:11]
	s_mov_b32 s9, 0
.Lmodk_loop:
	global_load_dword v162, v[122:123], off
	global_load_dword v163, v[124:125], off
	global_load_dword v164, v[126:127], off
	global_load_dword v165, v[128:129], off
	global_load_dword v166, v[130:131], off
	global_load_dword v167, v[132:133], off
	global_load_dword v168, v[134:135], off
	global_load_dword v169, v[136:137], off
	v_lshl_add_u64 v[122:123], v[122:123], 0, s[10:11]
	v_lshl_add_u64 v[124:125], v[124:125], 0, s[10:11]
	v_lshl_add_u64 v[126:127], v[126:127], 0, s[10:11]
	v_lshl_add_u64 v[128:129], v[128:129], 0, s[10:11]
	v_lshl_add_u64 v[130:131], v[130:131], 0, s[10:11]
	v_lshl_add_u64 v[132:133], v[132:133], 0, s[10:11]
	v_lshl_add_u64 v[134:135], v[134:135], 0, s[10:11]
	v_lshl_add_u64 v[136:137], v[136:137], 0, s[10:11]
	ds_read_b128 v[46:49], v45 offset:0
	ds_read_b128 v[50:53], v45 offset:16
	ds_read_b128 v[54:57], v45 offset:4096
	ds_read_b128 v[58:61], v45 offset:4112
	ds_read_b128 v[62:65], v45 offset:8192
	ds_read_b128 v[66:69], v45 offset:8208
	ds_read_b128 v[70:73], v45 offset:12288
	ds_read_b128 v[74:77], v45 offset:12304
	ds_read_b128 v[78:81], v45 offset:16384
	ds_read_b128 v[82:85], v45 offset:16400
	ds_read_b128 v[86:89], v45 offset:20480
	ds_read_b128 v[90:93], v45 offset:20496
	ds_read_b128 v[94:97], v45 offset:24576
	ds_read_b128 v[98:101], v45 offset:24592
	ds_read_b128 v[102:105], v45 offset:28672
	ds_read_b128 v[106:109], v45 offset:28688
	v_add_u32_e32 v45, 32, v45
	s_waitcnt vmcnt(24)
	s_waitcnt lgkmcnt(0)
	v_fma_f32 v2, v138, v46, v2
	v_fma_f32 v3, v138, v54, v3
	v_fma_f32 v4, v138, v62, v4
	v_fma_f32 v5, v138, v70, v5
	v_fma_f32 v6, v138, v78, v6
	v_fma_f32 v7, v138, v86, v7
	v_fma_f32 v8, v138, v94, v8
	v_fma_f32 v9, v138, v102, v9
	v_fma_f32 v2, v139, v47, v2
	v_fma_f32 v3, v139, v55, v3
	v_fma_f32 v4, v139, v63, v4
	v_fma_f32 v5, v139, v71, v5
	v_fma_f32 v6, v139, v79, v6
	v_fma_f32 v7, v139, v87, v7
	v_fma_f32 v8, v139, v95, v8
	v_fma_f32 v9, v139, v103, v9
	v_fma_f32 v2, v140, v48, v2
	v_fma_f32 v3, v140, v56, v3
	v_fma_f32 v4, v140, v64, v4
	v_fma_f32 v5, v140, v72, v5
	v_fma_f32 v6, v140, v80, v6
	v_fma_f32 v7, v140, v88, v7
	v_fma_f32 v8, v140, v96, v8
	v_fma_f32 v9, v140, v104, v9
	v_fma_f32 v2, v141, v49, v2
	v_fma_f32 v3, v141, v57, v3
	v_fma_f32 v4, v141, v65, v4
	v_fma_f32 v5, v141, v73, v5
	v_fma_f32 v6, v141, v81, v6
	v_fma_f32 v7, v141, v89, v7
	v_fma_f32 v8, v141, v97, v8
	v_fma_f32 v9, v141, v105, v9
	v_fma_f32 v2, v142, v50, v2
	v_fma_f32 v3, v142, v58, v3
	v_fma_f32 v4, v142, v66, v4
	v_fma_f32 v5, v142, v74, v5
	v_fma_f32 v6, v142, v82, v6
	v_fma_f32 v7, v142, v90, v7
	v_fma_f32 v8, v142, v98, v8
	v_fma_f32 v9, v142, v106, v9
	v_fma_f32 v2, v143, v51, v2
	v_fma_f32 v3, v143, v59, v3
	v_fma_f32 v4, v143, v67, v4
	v_fma_f32 v5, v143, v75, v5
	v_fma_f32 v6, v143, v83, v6
	v_fma_f32 v7, v143, v91, v7
	v_fma_f32 v8, v143, v99, v8
	v_fma_f32 v9, v143, v107, v9
	v_fma_f32 v2, v144, v52, v2
	v_fma_f32 v3, v144, v60, v3
	v_fma_f32 v4, v144, v68, v4
	v_fma_f32 v5, v144, v76, v5
	v_fma_f32 v6, v144, v84, v6
	v_fma_f32 v7, v144, v92, v7
	v_fma_f32 v8, v144, v100, v8
	v_fma_f32 v9, v144, v108, v9
	v_fma_f32 v2, v145, v53, v2
	v_fma_f32 v3, v145, v61, v3
	v_fma_f32 v4, v145, v69, v4
	v_fma_f32 v5, v145, v77, v5
	v_fma_f32 v6, v145, v85, v6
	v_fma_f32 v7, v145, v93, v7
	v_fma_f32 v8, v145, v101, v8
	v_fma_f32 v9, v145, v109, v9
	global_load_dword v138, v[122:123], off
	global_load_dword v139, v[124:125], off
	global_load_dword v140, v[126:127], off
	global_load_dword v141, v[128:129], off
	global_load_dword v142, v[130:131], off
	global_load_dword v143, v[132:133], off
	global_load_dword v144, v[134:135], off
	global_load_dword v145, v[136:137], off
	v_lshl_add_u64 v[122:123], v[122:123], 0, s[10:11]
	v_lshl_add_u64 v[124:125], v[124:125], 0, s[10:11]
	v_lshl_add_u64 v[126:127], v[126:127], 0, s[10:11]
	v_lshl_add_u64 v[128:129], v[128:129], 0, s[10:11]
	v_lshl_add_u64 v[130:131], v[130:131], 0, s[10:11]
	v_lshl_add_u64 v[132:133], v[132:133], 0, s[10:11]
	v_lshl_add_u64 v[134:135], v[134:135], 0, s[10:11]
	v_lshl_add_u64 v[136:137], v[136:137], 0, s[10:11]
	ds_read_b128 v[46:49], v45 offset:0
	ds_read_b128 v[50:53], v45 offset:16
	ds_read_b128 v[54:57], v45 offset:4096
	ds_read_b128 v[58:61], v45 offset:4112
	ds_read_b128 v[62:65], v45 offset:8192
	ds_read_b128 v[66:69], v45 offset:8208
	ds_read_b128 v[70:73], v45 offset:12288
	ds_read_b128 v[74:77], v45 offset:12304
	ds_read_b128 v[78:81], v45 offset:16384
	ds_read_b128 v[82:85], v45 offset:16400
	ds_read_b128 v[86:89], v45 offset:20480
	ds_read_b128 v[90:93], v45 offset:20496
	ds_read_b128 v[94:97], v45 offset:24576
	ds_read_b128 v[98:101], v45 offset:24592
	ds_read_b128 v[102:105], v45 offset:28672
	ds_read_b128 v[106:109], v45 offset:28688
	v_add_u32_e32 v45, 32, v45
	s_waitcnt vmcnt(24)
	s_waitcnt lgkmcnt(0)
	v_fma_f32 v2, v146, v46, v2
	v_fma_f32 v3, v146, v54, v3
	v_fma_f32 v4, v146, v62, v4
	v_fma_f32 v5, v146, v70, v5
	v_fma_f32 v6, v146, v78, v6
	v_fma_f32 v7, v146, v86, v7
	v_fma_f32 v8, v146, v94, v8
	v_fma_f32 v9, v146, v102, v9
	v_fma_f32 v2, v147, v47, v2
	v_fma_f32 v3, v147, v55, v3
	v_fma_f32 v4, v147, v63, v4
	v_fma_f32 v5, v147, v71, v5
	v_fma_f32 v6, v147, v79, v6
	v_fma_f32 v7, v147, v87, v7
	v_fma_f32 v8, v147, v95, v8
	v_fma_f32 v9, v147, v103, v9
	v_fma_f32 v2, v148, v48, v2
	v_fma_f32 v3, v148, v56, v3
	v_fma_f32 v4, v148, v64, v4
	v_fma_f32 v5, v148, v72, v5
	v_fma_f32 v6, v148, v80, v6
	v_fma_f32 v7, v148, v88, v7
	v_fma_f32 v8, v148, v96, v8
	v_fma_f32 v9, v148, v104, v9
	v_fma_f32 v2, v149, v49, v2
	v_fma_f32 v3, v149, v57, v3
	v_fma_f32 v4, v149, v65, v4
	v_fma_f32 v5, v149, v73, v5
	v_fma_f32 v6, v149, v81, v6
	v_fma_f32 v7, v149, v89, v7
	v_fma_f32 v8, v149, v97, v8
	v_fma_f32 v9, v149, v105, v9
	v_fma_f32 v2, v150, v50, v2
	v_fma_f32 v3, v150, v58, v3
	v_fma_f32 v4, v150, v66, v4
	v_fma_f32 v5, v150, v74, v5
	v_fma_f32 v6, v150, v82, v6
	v_fma_f32 v7, v150, v90, v7
	v_fma_f32 v8, v150, v98, v8
	v_fma_f32 v9, v150, v106, v9
	v_fma_f32 v2, v151, v51, v2
	v_fma_f32 v3, v151, v59, v3
	v_fma_f32 v4, v151, v67, v4
	v_fma_f32 v5, v151, v75, v5
	v_fma_f32 v6, v151, v83, v6
	v_fma_f32 v7, v151, v91, v7
	v_fma_f32 v8, v151, v99, v8
	v_fma_f32 v9, v151, v107, v9
	v_fma_f32 v2, v152, v52, v2
	v_fma_f32 v3, v152, v60, v3
	v_fma_f32 v4, v152, v68, v4
	v_fma_f32 v5, v152, v76, v5
	v_fma_f32 v6, v152, v84, v6
	v_fma_f32 v7, v152, v92, v7
	v_fma_f32 v8, v152, v100, v8
	v_fma_f32 v9, v152, v108, v9
	v_fma_f32 v2, v153, v53, v2
	v_fma_f32 v3, v153, v61, v3
	v_fma_f32 v4, v153, v69, v4
	v_fma_f32 v5, v153, v77, v5
	v_fma_f32 v6, v153, v85, v6
	v_fma_f32 v7, v153, v93, v7
	v_fma_f32 v8, v153, v101, v8
	v_fma_f32 v9, v153, v109, v9
	global_load_dword v146, v[122:123], off
	global_load_dword v147, v[124:125], off
	global_load_dword v148, v[126:127], off
	global_load_dword v149, v[128:129], off
	global_load_dword v150, v[130:131], off
	global_load_dword v151, v[132:133], off
	global_load_dword v152, v[134:135], off
	global_load_dword v153, v[136:137], off
	v_lshl_add_u64 v[122:123], v[122:123], 0, s[10:11]
	v_lshl_add_u64 v[124:125], v[124:125], 0, s[10:11]
	v_lshl_add_u64 v[126:127], v[126:127], 0, s[10:11]
	v_lshl_add_u64 v[128:129], v[128:129], 0, s[10:11]
	v_lshl_add_u64 v[130:131], v[130:131], 0, s[10:11]
	v_lshl_add_u64 v[132:133], v[132:133], 0, s[10:11]
	v_lshl_add_u64 v[134:135], v[134:135], 0, s[10:11]
	v_lshl_add_u64 v[136:137], v[136:137], 0, s[10:11]
	ds_read_b128 v[46:49], v45 offset:0
	ds_read_b128 v[50:53], v45 offset:16
	ds_read_b128 v[54:57], v45 offset:4096
	ds_read_b128 v[58:61], v45 offset:4112
	ds_read_b128 v[62:65], v45 offset:8192
	ds_read_b128 v[66:69], v45 offset:8208
	ds_read_b128 v[70:73], v45 offset:12288
	ds_read_b128 v[74:77], v45 offset:12304
	ds_read_b128 v[78:81], v45 offset:16384
	ds_read_b128 v[82:85], v45 offset:16400
	ds_read_b128 v[86:89], v45 offset:20480
	ds_read_b128 v[90:93], v45 offset:20496
	ds_read_b128 v[94:97], v45 offset:24576
	ds_read_b128 v[98:101], v45 offset:24592
	ds_read_b128 v[102:105], v45 offset:28672
	ds_read_b128 v[106:109], v45 offset:28688
	v_add_u32_e32 v45, 32, v45
	s_waitcnt vmcnt(24)
	s_waitcnt lgkmcnt(0)
	v_fma_f32 v2, v154, v46, v2
	v_fma_f32 v3, v154, v54, v3
	v_fma_f32 v4, v154, v62, v4
	v_fma_f32 v5, v154, v70, v5
	v_fma_f32 v6, v154, v78, v6
	v_fma_f32 v7, v154, v86, v7
	v_fma_f32 v8, v154, v94, v8
	v_fma_f32 v9, v154, v102, v9
	v_fma_f32 v2, v155, v47, v2
	v_fma_f32 v3, v155, v55, v3
	v_fma_f32 v4, v155, v63, v4
	v_fma_f32 v5, v155, v71, v5
	v_fma_f32 v6, v155, v79, v6
	v_fma_f32 v7, v155, v87, v7
	v_fma_f32 v8, v155, v95, v8
	v_fma_f32 v9, v155, v103, v9
	v_fma_f32 v2, v156, v48, v2
	v_fma_f32 v3, v156, v56, v3
	v_fma_f32 v4, v156, v64, v4
	v_fma_f32 v5, v156, v72, v5
	v_fma_f32 v6, v156, v80, v6
	v_fma_f32 v7, v156, v88, v7
	v_fma_f32 v8, v156, v96, v8
	v_fma_f32 v9, v156, v104, v9
	v_fma_f32 v2, v157, v49, v2
	v_fma_f32 v3, v157, v57, v3
	v_fma_f32 v4, v157, v65, v4
	v_fma_f32 v5, v157, v73, v5
	v_fma_f32 v6, v157, v81, v6
	v_fma_f32 v7, v157, v89, v7
	v_fma_f32 v8, v157, v97, v8
	v_fma_f32 v9, v157, v105, v9
	v_fma_f32 v2, v158, v50, v2
	v_fma_f32 v3, v158, v58, v3
	v_fma_f32 v4, v158, v66, v4
	v_fma_f32 v5, v158, v74, v5
	v_fma_f32 v6, v158, v82, v6
	v_fma_f32 v7, v158, v90, v7
	v_fma_f32 v8, v158, v98, v8
	v_fma_f32 v9, v158, v106, v9
	v_fma_f32 v2, v159, v51, v2
	v_fma_f32 v3, v159, v59, v3
	v_fma_f32 v4, v159, v67, v4
	v_fma_f32 v5, v159, v75, v5
	v_fma_f32 v6, v159, v83, v6
	v_fma_f32 v7, v159, v91, v7
	v_fma_f32 v8, v159, v99, v8
	v_fma_f32 v9, v159, v107, v9
	v_fma_f32 v2, v160, v52, v2
	v_fma_f32 v3, v160, v60, v3
	v_fma_f32 v4, v160, v68, v4
	v_fma_f32 v5, v160, v76, v5
	v_fma_f32 v6, v160, v84, v6
	v_fma_f32 v7, v160, v92, v7
	v_fma_f32 v8, v160, v100, v8
	v_fma_f32 v9, v160, v108, v9
	v_fma_f32 v2, v161, v53, v2
	v_fma_f32 v3, v161, v61, v3
	v_fma_f32 v4, v161, v69, v4
	v_fma_f32 v5, v161, v77, v5
	v_fma_f32 v6, v161, v85, v6
	v_fma_f32 v7, v161, v93, v7
	v_fma_f32 v8, v161, v101, v8
	v_fma_f32 v9, v161, v109, v9
	global_load_dword v154, v[122:123], off
	global_load_dword v155, v[124:125], off
	global_load_dword v156, v[126:127], off
	global_load_dword v157, v[128:129], off
	global_load_dword v158, v[130:131], off
	global_load_dword v159, v[132:133], off
	global_load_dword v160, v[134:135], off
	global_load_dword v161, v[136:137], off
	v_lshl_add_u64 v[122:123], v[122:123], 0, s[10:11]
	v_lshl_add_u64 v[124:125], v[124:125], 0, s[10:11]
	v_lshl_add_u64 v[126:127], v[126:127], 0, s[10:11]
	v_lshl_add_u64 v[128:129], v[128:129], 0, s[10:11]
	v_lshl_add_u64 v[130:131], v[130:131], 0, s[10:11]
	v_lshl_add_u64 v[132:133], v[132:133], 0, s[10:11]
	v_lshl_add_u64 v[134:135], v[134:135], 0, s[10:11]
	v_lshl_add_u64 v[136:137], v[136:137], 0, s[10:11]
	ds_read_b128 v[46:49], v45 offset:0
	ds_read_b128 v[50:53], v45 offset:16
	ds_read_b128 v[54:57], v45 offset:4096
	ds_read_b128 v[58:61], v45 offset:4112
	ds_read_b128 v[62:65], v45 offset:8192
	ds_read_b128 v[66:69], v45 offset:8208
	ds_read_b128 v[70:73], v45 offset:12288
	ds_read_b128 v[74:77], v45 offset:12304
	ds_read_b128 v[78:81], v45 offset:16384
	ds_read_b128 v[82:85], v45 offset:16400
	ds_read_b128 v[86:89], v45 offset:20480
	ds_read_b128 v[90:93], v45 offset:20496
	ds_read_b128 v[94:97], v45 offset:24576
	ds_read_b128 v[98:101], v45 offset:24592
	ds_read_b128 v[102:105], v45 offset:28672
	ds_read_b128 v[106:109], v45 offset:28688
	v_add_u32_e32 v45, 32, v45
	s_waitcnt vmcnt(24)
	s_waitcnt lgkmcnt(0)
	v_fma_f32 v2, v162, v46, v2
	v_fma_f32 v3, v162, v54, v3
	v_fma_f32 v4, v162, v62, v4
	v_fma_f32 v5, v162, v70, v5
	v_fma_f32 v6, v162, v78, v6
	v_fma_f32 v7, v162, v86, v7
	v_fma_f32 v8, v162, v94, v8
	v_fma_f32 v9, v162, v102, v9
	v_fma_f32 v2, v163, v47, v2
	v_fma_f32 v3, v163, v55, v3
	v_fma_f32 v4, v163, v63, v4
	v_fma_f32 v5, v163, v71, v5
	v_fma_f32 v6, v163, v79, v6
	v_fma_f32 v7, v163, v87, v7
	v_fma_f32 v8, v163, v95, v8
	v_fma_f32 v9, v163, v103, v9
	v_fma_f32 v2, v164, v48, v2
	v_fma_f32 v3, v164, v56, v3
	v_fma_f32 v4, v164, v64, v4
	v_fma_f32 v5, v164, v72, v5
	v_fma_f32 v6, v164, v80, v6
	v_fma_f32 v7, v164, v88, v7
	v_fma_f32 v8, v164, v96, v8
	v_fma_f32 v9, v164, v104, v9
	v_fma_f32 v2, v165, v49, v2
	v_fma_f32 v3, v165, v57, v3
	v_fma_f32 v4, v165, v65, v4
	v_fma_f32 v5, v165, v73, v5
	v_fma_f32 v6, v165, v81, v6
	v_fma_f32 v7, v165, v89, v7
	v_fma_f32 v8, v165, v97, v8
	v_fma_f32 v9, v165, v105, v9
	v_fma_f32 v2, v166, v50, v2
	v_fma_f32 v3, v166, v58, v3
	v_fma_f32 v4, v166, v66, v4
	v_fma_f32 v5, v166, v74, v5
	v_fma_f32 v6, v166, v82, v6
	v_fma_f32 v7, v166, v90, v7
	v_fma_f32 v8, v166, v98, v8
	v_fma_f32 v9, v166, v106, v9
	v_fma_f32 v2, v167, v51, v2
	v_fma_f32 v3, v167, v59, v3
	v_fma_f32 v4, v167, v67, v4
	v_fma_f32 v5, v167, v75, v5
	v_fma_f32 v6, v167, v83, v6
	v_fma_f32 v7, v167, v91, v7
	v_fma_f32 v8, v167, v99, v8
	v_fma_f32 v9, v167, v107, v9
	v_fma_f32 v2, v168, v52, v2
	v_fma_f32 v3, v168, v60, v3
	v_fma_f32 v4, v168, v68, v4
	v_fma_f32 v5, v168, v76, v5
	v_fma_f32 v6, v168, v84, v6
	v_fma_f32 v7, v168, v92, v7
	v_fma_f32 v8, v168, v100, v8
	v_fma_f32 v9, v168, v108, v9
	v_fma_f32 v2, v169, v53, v2
	v_fma_f32 v3, v169, v61, v3
	v_fma_f32 v4, v169, v69, v4
	v_fma_f32 v5, v169, v77, v5
	v_fma_f32 v6, v169, v85, v6
	v_fma_f32 v7, v169, v93, v7
	v_fma_f32 v8, v169, v101, v8
	v_fma_f32 v9, v169, v109, v9
	s_add_u32 s9, s9, 1
	s_cmp_lt_u32 s9, 7
	s_cbranch_scc1 .Lmodk_loop
	global_load_dword v162, v[122:123], off
	global_load_dword v163, v[124:125], off
	global_load_dword v164, v[126:127], off
	global_load_dword v165, v[128:129], off
	global_load_dword v166, v[130:131], off
	global_load_dword v167, v[132:133], off
	global_load_dword v168, v[134:135], off
	global_load_dword v169, v[136:137], off
	v_lshl_add_u64 v[122:123], v[122:123], 0, s[10:11]
	v_lshl_add_u64 v[124:125], v[124:125], 0, s[10:11]
	v_lshl_add_u64 v[126:127], v[126:127], 0, s[10:11]
	v_lshl_add_u64 v[128:129], v[128:129], 0, s[10:11]
	v_lshl_add_u64 v[130:131], v[130:131], 0, s[10:11]
	v_lshl_add_u64 v[132:133], v[132:133], 0, s[10:11]
	v_lshl_add_u64 v[134:135], v[134:135], 0, s[10:11]
	v_lshl_add_u64 v[136:137], v[136:137], 0, s[10:11]
	ds_read_b128 v[46:49], v45 offset:0
	ds_read_b128 v[50:53], v45 offset:16
	ds_read_b128 v[54:57], v45 offset:4096
	ds_read_b128 v[58:61], v45 offset:4112
	ds_read_b128 v[62:65], v45 offset:8192
	ds_read_b128 v[66:69], v45 offset:8208
	ds_read_b128 v[70:73], v45 offset:12288
	ds_read_b128 v[74:77], v45 offset:12304
	ds_read_b128 v[78:81], v45 offset:16384
	ds_read_b128 v[82:85], v45 offset:16400
	ds_read_b128 v[86:89], v45 offset:20480
	ds_read_b128 v[90:93], v45 offset:20496
	ds_read_b128 v[94:97], v45 offset:24576
	ds_read_b128 v[98:101], v45 offset:24592
	ds_read_b128 v[102:105], v45 offset:28672
	ds_read_b128 v[106:109], v45 offset:28688
	v_add_u32_e32 v45, 32, v45
	s_waitcnt vmcnt(24)
	s_waitcnt lgkmcnt(0)
	v_fma_f32 v2, v138, v46, v2
	v_fma_f32 v3, v138, v54, v3
	v_fma_f32 v4, v138, v62, v4
	v_fma_f32 v5, v138, v70, v5
	v_fma_f32 v6, v138, v78, v6
	v_fma_f32 v7, v138, v86, v7
	v_fma_f32 v8, v138, v94, v8
	v_fma_f32 v9, v138, v102, v9
	v_fma_f32 v2, v139, v47, v2
	v_fma_f32 v3, v139, v55, v3
	v_fma_f32 v4, v139, v63, v4
	v_fma_f32 v5, v139, v71, v5
	v_fma_f32 v6, v139, v79, v6
	v_fma_f32 v7, v139, v87, v7
	v_fma_f32 v8, v139, v95, v8
	v_fma_f32 v9, v139, v103, v9
	v_fma_f32 v2, v140, v48, v2
	v_fma_f32 v3, v140, v56, v3
	v_fma_f32 v4, v140, v64, v4
	v_fma_f32 v5, v140, v72, v5
	v_fma_f32 v6, v140, v80, v6
	v_fma_f32 v7, v140, v88, v7
	v_fma_f32 v8, v140, v96, v8
	v_fma_f32 v9, v140, v104, v9
	v_fma_f32 v2, v141, v49, v2
	v_fma_f32 v3, v141, v57, v3
	v_fma_f32 v4, v141, v65, v4
	v_fma_f32 v5, v141, v73, v5
	v_fma_f32 v6, v141, v81, v6
	v_fma_f32 v7, v141, v89, v7
	v_fma_f32 v8, v141, v97, v8
	v_fma_f32 v9, v141, v105, v9
	v_fma_f32 v2, v142, v50, v2
	v_fma_f32 v3, v142, v58, v3
	v_fma_f32 v4, v142, v66, v4
	v_fma_f32 v5, v142, v74, v5
	v_fma_f32 v6, v142, v82, v6
	v_fma_f32 v7, v142, v90, v7
	v_fma_f32 v8, v142, v98, v8
	v_fma_f32 v9, v142, v106, v9
	v_fma_f32 v2, v143, v51, v2
	v_fma_f32 v3, v143, v59, v3
	v_fma_f32 v4, v143, v67, v4
	v_fma_f32 v5, v143, v75, v5
	v_fma_f32 v6, v143, v83, v6
	v_fma_f32 v7, v143, v91, v7
	v_fma_f32 v8, v143, v99, v8
	v_fma_f32 v9, v143, v107, v9
	v_fma_f32 v2, v144, v52, v2
	v_fma_f32 v3, v144, v60, v3
	v_fma_f32 v4, v144, v68, v4
	v_fma_f32 v5, v144, v76, v5
	v_fma_f32 v6, v144, v84, v6
	v_fma_f32 v7, v144, v92, v7
	v_fma_f32 v8, v144, v100, v8
	v_fma_f32 v9, v144, v108, v9
	v_fma_f32 v2, v145, v53, v2
	v_fma_f32 v3, v145, v61, v3
	v_fma_f32 v4, v145, v69, v4
	v_fma_f32 v5, v145, v77, v5
	v_fma_f32 v6, v145, v85, v6
	v_fma_f32 v7, v145, v93, v7
	v_fma_f32 v8, v145, v101, v8
	v_fma_f32 v9, v145, v109, v9
	ds_read_b128 v[46:49], v45 offset:0
	ds_read_b128 v[50:53], v45 offset:16
	ds_read_b128 v[54:57], v45 offset:4096
	ds_read_b128 v[58:61], v45 offset:4112
	ds_read_b128 v[62:65], v45 offset:8192
	ds_read_b128 v[66:69], v45 offset:8208
	ds_read_b128 v[70:73], v45 offset:12288
	ds_read_b128 v[74:77], v45 offset:12304
	ds_read_b128 v[78:81], v45 offset:16384
	ds_read_b128 v[82:85], v45 offset:16400
	ds_read_b128 v[86:89], v45 offset:20480
	ds_read_b128 v[90:93], v45 offset:20496
	ds_read_b128 v[94:97], v45 offset:24576
	ds_read_b128 v[98:101], v45 offset:24592
	ds_read_b128 v[102:105], v45 offset:28672
	ds_read_b128 v[106:109], v45 offset:28688
	v_add_u32_e32 v45, 32, v45
	s_waitcnt vmcnt(16)
	s_waitcnt lgkmcnt(0)
	v_fma_f32 v2, v146, v46, v2
	v_fma_f32 v3, v146, v54, v3
	v_fma_f32 v4, v146, v62, v4
	v_fma_f32 v5, v146, v70, v5
	v_fma_f32 v6, v146, v78, v6
	v_fma_f32 v7, v146, v86, v7
	v_fma_f32 v8, v146, v94, v8
	v_fma_f32 v9, v146, v102, v9
	v_fma_f32 v2, v147, v47, v2
	v_fma_f32 v3, v147, v55, v3
	v_fma_f32 v4, v147, v63, v4
	v_fma_f32 v5, v147, v71, v5
	v_fma_f32 v6, v147, v79, v6
	v_fma_f32 v7, v147, v87, v7
	v_fma_f32 v8, v147, v95, v8
	v_fma_f32 v9, v147, v103, v9
	v_fma_f32 v2, v148, v48, v2
	v_fma_f32 v3, v148, v56, v3
	v_fma_f32 v4, v148, v64, v4
	v_fma_f32 v5, v148, v72, v5
	v_fma_f32 v6, v148, v80, v6
	v_fma_f32 v7, v148, v88, v7
	v_fma_f32 v8, v148, v96, v8
	v_fma_f32 v9, v148, v104, v9
	v_fma_f32 v2, v149, v49, v2
	v_fma_f32 v3, v149, v57, v3
	v_fma_f32 v4, v149, v65, v4
	v_fma_f32 v5, v149, v73, v5
	v_fma_f32 v6, v149, v81, v6
	v_fma_f32 v7, v149, v89, v7
	v_fma_f32 v8, v149, v97, v8
	v_fma_f32 v9, v149, v105, v9
	v_fma_f32 v2, v150, v50, v2
	v_fma_f32 v3, v150, v58, v3
	v_fma_f32 v4, v150, v66, v4
	v_fma_f32 v5, v150, v74, v5
	v_fma_f32 v6, v150, v82, v6
	v_fma_f32 v7, v150, v90, v7
	v_fma_f32 v8, v150, v98, v8
	v_fma_f32 v9, v150, v106, v9
	v_fma_f32 v2, v151, v51, v2
	v_fma_f32 v3, v151, v59, v3
	v_fma_f32 v4, v151, v67, v4
	v_fma_f32 v5, v151, v75, v5
	v_fma_f32 v6, v151, v83, v6
	v_fma_f32 v7, v151, v91, v7
	v_fma_f32 v8, v151, v99, v8
	v_fma_f32 v9, v151, v107, v9
	v_fma_f32 v2, v152, v52, v2
	v_fma_f32 v3, v152, v60, v3
	v_fma_f32 v4, v152, v68, v4
	v_fma_f32 v5, v152, v76, v5
	v_fma_f32 v6, v152, v84, v6
	v_fma_f32 v7, v152, v92, v7
	v_fma_f32 v8, v152, v100, v8
	v_fma_f32 v9, v152, v108, v9
	v_fma_f32 v2, v153, v53, v2
	v_fma_f32 v3, v153, v61, v3
	v_fma_f32 v4, v153, v69, v4
	v_fma_f32 v5, v153, v77, v5
	v_fma_f32 v6, v153, v85, v6
	v_fma_f32 v7, v153, v93, v7
	v_fma_f32 v8, v153, v101, v8
	v_fma_f32 v9, v153, v109, v9
	ds_read_b128 v[46:49], v45 offset:0
	ds_read_b128 v[50:53], v45 offset:16
	ds_read_b128 v[54:57], v45 offset:4096
	ds_read_b128 v[58:61], v45 offset:4112
	ds_read_b128 v[62:65], v45 offset:8192
	ds_read_b128 v[66:69], v45 offset:8208
	ds_read_b128 v[70:73], v45 offset:12288
	ds_read_b128 v[74:77], v45 offset:12304
	ds_read_b128 v[78:81], v45 offset:16384
	ds_read_b128 v[82:85], v45 offset:16400
	ds_read_b128 v[86:89], v45 offset:20480
	ds_read_b128 v[90:93], v45 offset:20496
	ds_read_b128 v[94:97], v45 offset:24576
	ds_read_b128 v[98:101], v45 offset:24592
	ds_read_b128 v[102:105], v45 offset:28672
	ds_read_b128 v[106:109], v45 offset:28688
	v_add_u32_e32 v45, 32, v45
	s_waitcnt vmcnt(8)
	s_waitcnt lgkmcnt(0)
	v_fma_f32 v2, v154, v46, v2
	v_fma_f32 v3, v154, v54, v3
	v_fma_f32 v4, v154, v62, v4
	v_fma_f32 v5, v154, v70, v5
	v_fma_f32 v6, v154, v78, v6
	v_fma_f32 v7, v154, v86, v7
	v_fma_f32 v8, v154, v94, v8
	v_fma_f32 v9, v154, v102, v9
	v_fma_f32 v2, v155, v47, v2
	v_fma_f32 v3, v155, v55, v3
	v_fma_f32 v4, v155, v63, v4
	v_fma_f32 v5, v155, v71, v5
	v_fma_f32 v6, v155, v79, v6
	v_fma_f32 v7, v155, v87, v7
	v_fma_f32 v8, v155, v95, v8
	v_fma_f32 v9, v155, v103, v9
	v_fma_f32 v2, v156, v48, v2
	v_fma_f32 v3, v156, v56, v3
	v_fma_f32 v4, v156, v64, v4
	v_fma_f32 v5, v156, v72, v5
	v_fma_f32 v6, v156, v80, v6
	v_fma_f32 v7, v156, v88, v7
	v_fma_f32 v8, v156, v96, v8
	v_fma_f32 v9, v156, v104, v9
	v_fma_f32 v2, v157, v49, v2
	v_fma_f32 v3, v157, v57, v3
	v_fma_f32 v4, v157, v65, v4
	v_fma_f32 v5, v157, v73, v5
	v_fma_f32 v6, v157, v81, v6
	v_fma_f32 v7, v157, v89, v7
	v_fma_f32 v8, v157, v97, v8
	v_fma_f32 v9, v157, v105, v9
	v_fma_f32 v2, v158, v50, v2
	v_fma_f32 v3, v158, v58, v3
	v_fma_f32 v4, v158, v66, v4
	v_fma_f32 v5, v158, v74, v5
	v_fma_f32 v6, v158, v82, v6
	v_fma_f32 v7, v158, v90, v7
	v_fma_f32 v8, v158, v98, v8
	v_fma_f32 v9, v158, v106, v9
	v_fma_f32 v2, v159, v51, v2
	v_fma_f32 v3, v159, v59, v3
	v_fma_f32 v4, v159, v67, v4
	v_fma_f32 v5, v159, v75, v5
	v_fma_f32 v6, v159, v83, v6
	v_fma_f32 v7, v159, v91, v7
	v_fma_f32 v8, v159, v99, v8
	v_fma_f32 v9, v159, v107, v9
	v_fma_f32 v2, v160, v52, v2
	v_fma_f32 v3, v160, v60, v3
	v_fma_f32 v4, v160, v68, v4
	v_fma_f32 v5, v160, v76, v5
	v_fma_f32 v6, v160, v84, v6
	v_fma_f32 v7, v160, v92, v7
	v_fma_f32 v8, v160, v100, v8
	v_fma_f32 v9, v160, v108, v9
	v_fma_f32 v2, v161, v53, v2
	v_fma_f32 v3, v161, v61, v3
	v_fma_f32 v4, v161, v69, v4
	v_fma_f32 v5, v161, v77, v5
	v_fma_f32 v6, v161, v85, v6
	v_fma_f32 v7, v161, v93, v7
	v_fma_f32 v8, v161, v101, v8
	v_fma_f32 v9, v161, v109, v9
	ds_read_b128 v[46:49], v45 offset:0
	ds_read_b128 v[50:53], v45 offset:16
	ds_read_b128 v[54:57], v45 offset:4096
	ds_read_b128 v[58:61], v45 offset:4112
	ds_read_b128 v[62:65], v45 offset:8192
	ds_read_b128 v[66:69], v45 offset:8208
	ds_read_b128 v[70:73], v45 offset:12288
	ds_read_b128 v[74:77], v45 offset:12304
	ds_read_b128 v[78:81], v45 offset:16384
	ds_read_b128 v[82:85], v45 offset:16400
	ds_read_b128 v[86:89], v45 offset:20480
	ds_read_b128 v[90:93], v45 offset:20496
	ds_read_b128 v[94:97], v45 offset:24576
	ds_read_b128 v[98:101], v45 offset:24592
	ds_read_b128 v[102:105], v45 offset:28672
	ds_read_b128 v[106:109], v45 offset:28688
	v_add_u32_e32 v45, 32, v45
	s_waitcnt vmcnt(0)
	s_waitcnt lgkmcnt(0)
	v_fma_f32 v2, v162, v46, v2
	v_fma_f32 v3, v162, v54, v3
	v_fma_f32 v4, v162, v62, v4
	v_fma_f32 v5, v162, v70, v5
	v_fma_f32 v6, v162, v78, v6
	v_fma_f32 v7, v162, v86, v7
	v_fma_f32 v8, v162, v94, v8
	v_fma_f32 v9, v162, v102, v9
	v_fma_f32 v2, v163, v47, v2
	v_fma_f32 v3, v163, v55, v3
	v_fma_f32 v4, v163, v63, v4
	v_fma_f32 v5, v163, v71, v5
	v_fma_f32 v6, v163, v79, v6
	v_fma_f32 v7, v163, v87, v7
	v_fma_f32 v8, v163, v95, v8
	v_fma_f32 v9, v163, v103, v9
	v_fma_f32 v2, v164, v48, v2
	v_fma_f32 v3, v164, v56, v3
	v_fma_f32 v4, v164, v64, v4
	v_fma_f32 v5, v164, v72, v5
	v_fma_f32 v6, v164, v80, v6
	v_fma_f32 v7, v164, v88, v7
	v_fma_f32 v8, v164, v96, v8
	v_fma_f32 v9, v164, v104, v9
	v_fma_f32 v2, v165, v49, v2
	v_fma_f32 v3, v165, v57, v3
	v_fma_f32 v4, v165, v65, v4
	v_fma_f32 v5, v165, v73, v5
	v_fma_f32 v6, v165, v81, v6
	v_fma_f32 v7, v165, v89, v7
	v_fma_f32 v8, v165, v97, v8
	v_fma_f32 v9, v165, v105, v9
	v_fma_f32 v2, v166, v50, v2
	v_fma_f32 v3, v166, v58, v3
	v_fma_f32 v4, v166, v66, v4
	v_fma_f32 v5, v166, v74, v5
	v_fma_f32 v6, v166, v82, v6
	v_fma_f32 v7, v166, v90, v7
	v_fma_f32 v8, v166, v98, v8
	v_fma_f32 v9, v166, v106, v9
	v_fma_f32 v2, v167, v51, v2
	v_fma_f32 v3, v167, v59, v3
	v_fma_f32 v4, v167, v67, v4
	v_fma_f32 v5, v167, v75, v5
	v_fma_f32 v6, v167, v83, v6
	v_fma_f32 v7, v167, v91, v7
	v_fma_f32 v8, v167, v99, v8
	v_fma_f32 v9, v167, v107, v9
	v_fma_f32 v2, v168, v52, v2
	v_fma_f32 v3, v168, v60, v3
	v_fma_f32 v4, v168, v68, v4
	v_fma_f32 v5, v168, v76, v5
	v_fma_f32 v6, v168, v84, v6
	v_fma_f32 v7, v168, v92, v7
	v_fma_f32 v8, v168, v100, v8
	v_fma_f32 v9, v168, v108, v9
	v_fma_f32 v2, v169, v53, v2
	v_fma_f32 v3, v169, v61, v3
	v_fma_f32 v4, v169, v69, v4
	v_fma_f32 v5, v169, v77, v5
	v_fma_f32 v6, v169, v85, v6
	v_fma_f32 v7, v169, v93, v7
	v_fma_f32 v8, v169, v101, v8
	v_fma_f32 v9, v169, v109, v9
	s_mul_i32 s9, s6, 0xc00
	s_add_i32 s9, s9, s8
	ds_write_b128 v39, v[2:5] offset:32768
	ds_write_b128 v39, v[6:9] offset:32784
	v_add_u32_e32 v2, s9, v26
	v_readlane_b32 s36, v237, 10
	v_ashrrev_i32_e32 v3, 31, v2
	v_readlane_b32 s46, v237, 20
	v_readlane_b32 s47, v237, 21
	v_add_u32_e32 v4, s9, v28
	v_ashrrev_i32_e32 v5, 31, v4
	v_lshl_add_u64 v[2:3], v[2:3], 2, s[46:47]
	s_waitcnt lgkmcnt(0)
	s_barrier
	v_lshl_add_u64 v[4:5], v[4:5], 2, s[46:47]
	global_load_dword v12, v[2:3], off
	global_load_dword v13, v[4:5], off
	ds_read2st64_b32 v[2:3], v44 offset0:128 offset1:132
	ds_read2st64_b32 v[4:5], v40 offset0:136 offset1:144
	ds_read2st64_b32 v[6:7], v41 offset0:136 offset1:144
	ds_read_b32 v14, v40 offset:38912
	ds_read_b32 v15, v41 offset:38912
	v_lshl_or_b32 v8, s6, 3, v24
	v_mad_u64_u32 v[8:9], s[10:11], v8, s14, v[34:35]
	s_waitcnt lgkmcnt(3)
	v_add_f32_e32 v2, v2, v4
	s_ashr_i32 s9, s8, 31
	v_mad_i32_i24 v9, s7, v43, v9
	s_waitcnt lgkmcnt(2)
	v_add_f32_e32 v3, v3, v6
	v_add_f32_e32 v2, v2, v5
	s_add_i32 s12, s12, s26
	v_lshl_add_u64 v[8:9], s[8:9], 2, v[8:9]
	v_add_f32_e32 v3, v3, v7
	s_waitcnt lgkmcnt(1)
	v_add_f32_e32 v2, v2, v14
	s_cmpk_gt_i32 s12, 0xbf
	v_lshl_add_u64 v[10:11], v[26:27], 2, v[8:9]
	s_waitcnt lgkmcnt(0)
	v_add_f32_e32 v3, v3, v15
	s_mov_b64 s[6:7], -1
	v_readlane_b32 s37, v237, 11
	v_readlane_b32 s38, v237, 12
	v_readlane_b32 s39, v237, 13
	v_readlane_b32 s40, v237, 14
	v_readlane_b32 s41, v237, 15
	v_readlane_b32 s42, v237, 16
	v_readlane_b32 s43, v237, 17
	v_readlane_b32 s44, v237, 18
	v_readlane_b32 s45, v237, 19
	v_readlane_b32 s48, v237, 22
	v_readlane_b32 s49, v237, 23
	v_readlane_b32 s50, v237, 24
	v_readlane_b32 s51, v237, 25
	v_lshl_add_u64 v[8:9], v[28:29], 2, v[8:9]
	s_waitcnt vmcnt(1)
	v_add_f32_e32 v2, v2, v12
	s_waitcnt vmcnt(0)
	v_add_f32_e32 v3, v3, v13
	global_store_dword v[10:11], v2, off
	global_store_dword v[8:9], v3, off
	s_barrier
	s_cbranch_scc0 .LBB0_23
